# v7 + grid barrier: waiters poll the cross-XCD arrival counter; each workgroup invalidates its L1 when it closes (before arriving) instead of after the release
# speedup vs baseline: 1.0155x; 1.0155x over previous
.LBB0_169:
	s_cmp_gt_i32 s91, 1
	s_cselect_b64 s[4:5], -1, 0
	s_and_b64 s[6:7], s[10:11], s[4:5]
	s_andn2_b64 vcc, exec, s[6:7]
	s_cbranch_vccnz .LBB0_223
	s_waitcnt vmcnt(0)
	s_waitcnt lgkmcnt(0)
	s_barrier
	s_and_saveexec_b64 s[6:7], s[18:19]
	s_cbranch_execz .LBB0_222
	s_add_i32 s2, 0, 0x113f0
	v_mov_b32_e32 v0, s2
	buffer_inv sc1
	s_waitcnt vmcnt(0) expcnt(0) lgkmcnt(0)
	ds_read_b32 v2, v0
	s_add_i32 s2, 0, 0x113f4
	v_mov_b32_e32 v0, s2
	ds_read_b32 v0, v0
	s_waitcnt lgkmcnt(1)
	v_cmp_ne_u32_e32 vcc, 0, v2
	s_cbranch_vccnz .LBB0_186
	s_add_u32 s8, s88, 0xeaf0200
	s_addc_u32 s9, s89, 0
	s_add_u32 s10, s88, 0xeaf0400
	s_addc_u32 s11, s89, 0
	s_add_u32 s12, s88, 0xeaf0500
	s_addc_u32 s13, s89, 0
	s_add_u32 s14, s88, 0xeaf0600
	s_addc_u32 s15, s89, 0
	s_add_u32 s16, s88, 0xeaf0700
	s_addc_u32 s17, s89, 0
	s_add_u32 s20, s88, 0xeaf0800
	s_addc_u32 s21, s89, 0
	s_add_u32 s22, s88, 0xeaf0900
	s_addc_u32 s23, s89, 0
	s_add_u32 s24, s88, 0xeaf0a00
	s_addc_u32 s25, s89, 0
	s_add_u32 s26, s88, 0xeaf0b00
	s_addc_u32 s27, s89, 0
	s_add_u32 s28, s88, 0xeaf0c00
	s_addc_u32 s29, s89, 0
	s_add_u32 s30, s88, 0xeaf0d00
	s_addc_u32 s31, s89, 0
	s_add_u32 s34, s88, 0xeaf0e00
	s_addc_u32 s35, s89, 0
	s_add_u32 s36, s88, 0xeaf0f00
	s_addc_u32 s37, s89, 0
	s_add_u32 s38, s88, 0xeaf1000
	s_addc_u32 s39, s89, 0
	s_add_u32 s40, s88, 0xeaf1100
	s_addc_u32 s41, s89, 0
	s_add_u32 s42, s88, 0xeaf1200
	s_addc_u32 s43, s89, 0
	s_mul_i32 s2, s93, s95
	s_add_u32 s44, s88, 0xeaf1300
	s_mul_i32 s2, s2, s92
	s_addc_u32 s45, s89, 0
	s_mov_b32 s33, 1
	v_mov_b32_e32 v16, 0
	s_branch .LBB0_174

.LBB0_188:
	s_or_b64 exec, exec, s[12:13]
	v_cvt_f32_u32_e32 v4, v2
	s_waitcnt vmcnt(0)
	v_readfirstlane_b32 s2, v3
	v_sub_u32_e32 v3, 0, v2
	v_rcp_iflag_f32_e32 v4, v4
	v_add_u32_e32 v5, s2, v1
	v_mul_f32_e32 v4, 0x4f7ffffe, v4
	v_cvt_u32_f32_e32 v4, v4
	v_mul_lo_u32 v1, v3, v4
	v_mul_hi_u32 v1, v4, v1
	v_add_u32_e32 v1, v4, v1
	v_mul_hi_u32 v1, v5, v1
	v_mul_lo_u32 v3, v1, v2
	v_sub_u32_e32 v3, v5, v3
	v_add_u32_e32 v4, 1, v1
	v_cmp_ge_u32_e32 vcc, v3, v2
	s_nop 1
	v_cndmask_b32_e32 v1, v1, v4, vcc
	v_sub_u32_e32 v4, v3, v2
	v_cndmask_b32_e32 v3, v3, v4, vcc
	v_add_u32_e32 v4, 1, v1
	v_cmp_ge_u32_e32 vcc, v3, v2
	v_add_u32_e32 v3, 1, v5
	s_nop 0
	v_cndmask_b32_e32 v1, v1, v4, vcc
	v_mul_lo_u32 v4, v2, v1
	v_add_u32_e32 v2, v4, v2
	v_cmp_ne_u32_e32 vcc, v3, v2
	s_and_saveexec_b64 s[10:11], vcc
	s_xor_b64 s[10:11], exec, s[10:11]
	s_cbranch_execz .LBB0_202
	s_waitcnt lgkmcnt(0)
	v_add_u32_e32 v1, 1, v1
	v_mul_lo_u32 v1, v1, v0
	v_mov_b32_e32 v0, 0
	s_add_u32 s16, s88, 0xeaf3400
	s_addc_u32 s17, s89, 0
	global_load_dword v0, v0, s[16:17] sc1
	s_waitcnt vmcnt(0)
	v_cmp_lt_u32_e32 vcc, v0, v1
	s_and_saveexec_b64 s[12:13], vcc
	s_cbranch_execz .LBB0_201
	s_add_u32 s14, s88, 0xeaf0200
	s_addc_u32 s15, s89, 0
	s_mov_b32 s2, 1
	s_mov_b64 s[20:21], 0
	v_mov_b32_e32 v0, 0
	s_branch .LBB0_192

.LBB0_194:
	global_load_dword v2, v0, s[16:17] sc1
	s_add_i32 s2, s2, 1
	s_mov_b64 s[26:27], -1
	s_waitcnt vmcnt(0)
	v_cmp_ge_u32_e32 vcc, v2, v1
	s_orn2_b64 s[24:25], vcc, exec
	s_branch .LBB0_191

.LBB0_201:
	s_or_b64 exec, exec, s[12:13]
	s_waitcnt vmcnt(0)
	s_waitcnt vmcnt(0)

.LBB0_205:
	s_or_b64 exec, exec, s[12:13]
	v_cvt_f32_u32_e32 v3, v0
	s_waitcnt vmcnt(0)
	v_readfirstlane_b32 s2, v2
	s_add_u32 s12, s88, 0xeaf3500
	s_addc_u32 s13, s89, 0
	v_rcp_iflag_f32_e32 v3, v3
	v_add_u32_e32 v1, s2, v1
	v_add_u32_e32 v4, 1, v1
	s_mov_b64 s[14:15], -1
	v_mul_f32_e32 v2, 0x4f7ffffe, v3
	v_cvt_u32_f32_e32 v2, v2
	v_sub_u32_e32 v3, 0, v0
	v_mul_lo_u32 v3, v3, v2
	v_mul_hi_u32 v3, v2, v3
	v_add_u32_e32 v2, v2, v3
	v_mul_hi_u32 v2, v1, v2
	v_mul_lo_u32 v3, v2, v0
	v_sub_u32_e32 v1, v1, v3
	v_add_u32_e32 v5, 1, v2
	v_cmp_ge_u32_e32 vcc, v1, v0
	v_sub_u32_e32 v3, v1, v0
	s_nop 0
	v_cndmask_b32_e32 v2, v2, v5, vcc
	v_cndmask_b32_e32 v1, v1, v3, vcc
	v_add_u32_e32 v3, 1, v2
	v_cmp_ge_u32_e32 vcc, v1, v0
	s_nop 1
	v_cndmask_b32_e32 v2, v2, v3, vcc
	v_mul_lo_u32 v1, v0, v2
	v_add_u32_e32 v0, v1, v0
	v_cmp_ne_u32_e32 vcc, v4, v0
	v_mov_b32_e32 v3, v0
	s_add_u32 s98, s88, 0xeaf3400
	s_addc_u32 s99, s89, 0
	v_mov_b64_e32 v[0:1], s[12:13]
	s_and_saveexec_b64 s[10:11], vcc
	s_cbranch_execz .LBB0_217
	v_mov_b32_e32 v0, 0
	global_load_dword v1, v0, s[98:99] sc1
	s_mov_b64 s[20:21], 0
	s_waitcnt vmcnt(0)
	v_cmp_lt_u32_e32 vcc, v1, v3
	s_and_saveexec_b64 s[16:17], vcc
	s_cbranch_execz .LBB0_216
	s_add_u32 s14, s88, 0xeaf0200
	s_addc_u32 s15, s89, 0
	s_mov_b32 s2, 1
	s_branch .LBB0_209

.LBB0_211:
	global_load_dword v1, v0, s[98:99] sc1
	s_add_i32 s2, s2, 1
	s_mov_b64 s[24:25], -1
	s_waitcnt vmcnt(0)
	v_cmp_ge_u32_e32 vcc, v1, v3
	s_orn2_b64 s[28:29], vcc, exec
	s_branch .LBB0_208

.LBB0_219:
	s_or_b64 exec, exec, s[10:11]
	s_mov_b64 s[10:11], exec
	v_mbcnt_lo_u32_b32 v0, s10, 0
	v_mbcnt_hi_u32_b32 v0, s11, v0
	v_cmp_eq_u32_e32 vcc, 0, v0
	s_waitcnt vmcnt(0)
	s_and_saveexec_b64 s[12:13], vcc
	s_cbranch_execz .LBB0_221
	s_bcnt1_i32_b64 s2, s[10:11]
	v_mov_b32_e32 v0, 0x2000
	v_mov_b32_e32 v1, s2
	global_atomic_add v0, v1, s[8:9] offset:1024

.LBB0_387:
	s_cmp_gt_i32 s91, 2
	s_cselect_b64 s[0:1], -1, 0
	s_and_b64 s[4:5], s[14:15], s[0:1]
	s_andn2_b64 vcc, exec, s[4:5]
	s_cbranch_vccnz .LBB0_441
	s_waitcnt vmcnt(0)
	s_waitcnt lgkmcnt(0)
	s_barrier
	s_and_saveexec_b64 s[4:5], s[18:19]
	s_cbranch_execz .LBB0_440
	s_add_i32 s2, 0, 0x113f0
	v_mov_b32_e32 v0, s2
	buffer_inv sc1
	s_waitcnt vmcnt(0) expcnt(0) lgkmcnt(0)
	ds_read_b32 v2, v0
	s_add_i32 s2, 0, 0x113f4
	v_mov_b32_e32 v0, s2
	ds_read_b32 v0, v0
	s_waitcnt lgkmcnt(1)
	v_cmp_ne_u32_e32 vcc, 0, v2
	s_cbranch_vccnz .LBB0_404
	s_add_u32 s6, s88, 0xeaf0200
	s_addc_u32 s7, s89, 0
	s_add_u32 s8, s88, 0xeaf0400
	s_addc_u32 s9, s89, 0
	s_add_u32 s10, s88, 0xeaf0500
	s_addc_u32 s11, s89, 0
	s_add_u32 s12, s88, 0xeaf0600
	s_addc_u32 s13, s89, 0
	s_add_u32 s14, s88, 0xeaf0700
	s_addc_u32 s15, s89, 0
	s_add_u32 s16, s88, 0xeaf0800
	s_addc_u32 s17, s89, 0
	s_add_u32 s20, s88, 0xeaf0900
	s_addc_u32 s21, s89, 0
	s_add_u32 s22, s88, 0xeaf0a00
	s_addc_u32 s23, s89, 0
	s_add_u32 s24, s88, 0xeaf0b00
	s_addc_u32 s25, s89, 0
	s_add_u32 s26, s88, 0xeaf0c00
	s_addc_u32 s27, s89, 0
	s_add_u32 s28, s88, 0xeaf0d00
	s_addc_u32 s29, s89, 0
	s_add_u32 s30, s88, 0xeaf0e00
	s_addc_u32 s31, s89, 0
	s_add_u32 s34, s88, 0xeaf0f00
	s_addc_u32 s35, s89, 0
	s_add_u32 s36, s88, 0xeaf1000
	s_addc_u32 s37, s89, 0
	s_add_u32 s38, s88, 0xeaf1100
	s_addc_u32 s39, s89, 0
	s_add_u32 s40, s88, 0xeaf1200
	s_addc_u32 s41, s89, 0
	s_mul_i32 s2, s93, s95
	s_add_u32 s42, s88, 0xeaf1300
	s_mul_i32 s2, s2, s92
	s_addc_u32 s43, s89, 0
	s_mov_b32 s33, 1
	v_mov_b32_e32 v16, 0
	s_branch .LBB0_392

.LBB0_406:
	s_or_b64 exec, exec, s[10:11]
	v_cvt_f32_u32_e32 v4, v2
	s_waitcnt vmcnt(0)
	v_readfirstlane_b32 s2, v3
	v_sub_u32_e32 v3, 0, v2
	v_rcp_iflag_f32_e32 v4, v4
	v_add_u32_e32 v5, s2, v1
	v_mul_f32_e32 v4, 0x4f7ffffe, v4
	v_cvt_u32_f32_e32 v4, v4
	v_mul_lo_u32 v1, v3, v4
	v_mul_hi_u32 v1, v4, v1
	v_add_u32_e32 v1, v4, v1
	v_mul_hi_u32 v1, v5, v1
	v_mul_lo_u32 v3, v1, v2
	v_sub_u32_e32 v3, v5, v3
	v_add_u32_e32 v4, 1, v1
	v_cmp_ge_u32_e32 vcc, v3, v2
	s_nop 1
	v_cndmask_b32_e32 v1, v1, v4, vcc
	v_sub_u32_e32 v4, v3, v2
	v_cndmask_b32_e32 v3, v3, v4, vcc
	v_add_u32_e32 v4, 1, v1
	v_cmp_ge_u32_e32 vcc, v3, v2
	v_add_u32_e32 v3, 1, v5
	s_nop 0
	v_cndmask_b32_e32 v1, v1, v4, vcc
	v_mul_lo_u32 v4, v2, v1
	v_add_u32_e32 v2, v4, v2
	v_cmp_ne_u32_e32 vcc, v3, v2
	s_and_saveexec_b64 s[8:9], vcc
	s_xor_b64 s[8:9], exec, s[8:9]
	s_cbranch_execz .LBB0_420
	s_waitcnt lgkmcnt(0)
	v_add_u32_e32 v1, 1, v1
	v_mul_lo_u32 v1, v1, v0
	v_mov_b32_e32 v0, 0
	s_add_u32 s14, s88, 0xeaf3400
	s_addc_u32 s15, s89, 0
	global_load_dword v0, v0, s[14:15] sc1
	s_waitcnt vmcnt(0)
	v_cmp_lt_u32_e32 vcc, v0, v1
	s_and_saveexec_b64 s[10:11], vcc
	s_cbranch_execz .LBB0_419
	s_add_u32 s12, s88, 0xeaf0200
	s_addc_u32 s13, s89, 0
	s_mov_b32 s2, 1
	s_mov_b64 s[16:17], 0
	v_mov_b32_e32 v0, 0
	s_branch .LBB0_410

.LBB0_412:
	global_load_dword v2, v0, s[14:15] sc1
	s_add_i32 s2, s2, 1
	s_mov_b64 s[24:25], -1
	s_waitcnt vmcnt(0)
	v_cmp_ge_u32_e32 vcc, v2, v1
	s_orn2_b64 s[22:23], vcc, exec
	s_branch .LBB0_409

.LBB0_419:
	s_or_b64 exec, exec, s[10:11]
	s_waitcnt vmcnt(0)
	s_waitcnt vmcnt(0)

.LBB0_423:
	s_or_b64 exec, exec, s[10:11]
	v_cvt_f32_u32_e32 v3, v0
	s_waitcnt vmcnt(0)
	v_readfirstlane_b32 s2, v2
	s_add_u32 s10, s88, 0xeaf3500
	s_addc_u32 s11, s89, 0
	v_rcp_iflag_f32_e32 v3, v3
	v_add_u32_e32 v1, s2, v1
	v_add_u32_e32 v4, 1, v1
	s_mov_b64 s[12:13], -1
	v_mul_f32_e32 v2, 0x4f7ffffe, v3
	v_cvt_u32_f32_e32 v2, v2
	v_sub_u32_e32 v3, 0, v0
	v_mul_lo_u32 v3, v3, v2
	v_mul_hi_u32 v3, v2, v3
	v_add_u32_e32 v2, v2, v3
	v_mul_hi_u32 v2, v1, v2
	v_mul_lo_u32 v3, v2, v0
	v_sub_u32_e32 v1, v1, v3
	v_add_u32_e32 v5, 1, v2
	v_cmp_ge_u32_e32 vcc, v1, v0
	v_sub_u32_e32 v3, v1, v0
	s_nop 0
	v_cndmask_b32_e32 v2, v2, v5, vcc
	v_cndmask_b32_e32 v1, v1, v3, vcc
	v_add_u32_e32 v3, 1, v2
	v_cmp_ge_u32_e32 vcc, v1, v0
	s_nop 1
	v_cndmask_b32_e32 v2, v2, v3, vcc
	v_mul_lo_u32 v1, v0, v2
	v_add_u32_e32 v0, v1, v0
	v_cmp_ne_u32_e32 vcc, v4, v0
	v_mov_b32_e32 v3, v0
	s_add_u32 s98, s88, 0xeaf3400
	s_addc_u32 s99, s89, 0
	v_mov_b64_e32 v[0:1], s[10:11]
	s_and_saveexec_b64 s[8:9], vcc
	s_cbranch_execz .LBB0_435
	v_mov_b32_e32 v0, 0
	global_load_dword v1, v0, s[98:99] sc1
	s_mov_b64 s[16:17], 0
	s_waitcnt vmcnt(0)
	v_cmp_lt_u32_e32 vcc, v1, v3
	s_and_saveexec_b64 s[14:15], vcc
	s_cbranch_execz .LBB0_434
	s_add_u32 s12, s88, 0xeaf0200
	s_addc_u32 s13, s89, 0
	s_mov_b32 s2, 1
	s_branch .LBB0_427

.LBB0_429:
	global_load_dword v1, v0, s[98:99] sc1
	s_add_i32 s2, s2, 1
	s_mov_b64 s[22:23], -1
	s_waitcnt vmcnt(0)
	v_cmp_ge_u32_e32 vcc, v1, v3
	s_orn2_b64 s[26:27], vcc, exec
	s_branch .LBB0_426

.LBB0_437:
	s_or_b64 exec, exec, s[8:9]
	s_mov_b64 s[8:9], exec
	v_mbcnt_lo_u32_b32 v0, s8, 0
	v_mbcnt_hi_u32_b32 v0, s9, v0
	v_cmp_eq_u32_e32 vcc, 0, v0
	s_waitcnt vmcnt(0)
	s_and_saveexec_b64 s[10:11], vcc
	s_cbranch_execz .LBB0_439
	s_bcnt1_i32_b64 s2, s[8:9]
	v_mov_b32_e32 v0, 0x2000
	v_mov_b32_e32 v1, s2
	global_atomic_add v0, v1, s[6:7] offset:1024

.LBB0_459:
	s_cmp_gt_i32 s91, 3
	s_cselect_b64 s[0:1], -1, 0
	s_and_b64 s[4:5], s[4:5], s[0:1]
	s_andn2_b64 vcc, exec, s[4:5]
	s_cbranch_vccnz .LBB0_513
	s_waitcnt vmcnt(0)
	s_waitcnt lgkmcnt(0)
	s_barrier
	s_and_saveexec_b64 s[4:5], s[18:19]
	s_cbranch_execz .LBB0_512
	s_add_i32 s2, 0, 0x113f0
	v_mov_b32_e32 v0, s2
	buffer_inv sc1
	s_waitcnt vmcnt(0) expcnt(0) lgkmcnt(0)
	ds_read_b32 v2, v0
	s_add_i32 s2, 0, 0x113f4
	v_mov_b32_e32 v0, s2
	ds_read_b32 v0, v0
	s_waitcnt lgkmcnt(1)
	v_cmp_ne_u32_e32 vcc, 0, v2
	s_cbranch_vccnz .LBB0_476
	s_add_u32 s6, s88, 0xeaf0200
	s_addc_u32 s7, s89, 0
	s_add_u32 s8, s88, 0xeaf0400
	s_addc_u32 s9, s89, 0
	s_add_u32 s10, s88, 0xeaf0500
	s_addc_u32 s11, s89, 0
	s_add_u32 s12, s88, 0xeaf0600
	s_addc_u32 s13, s89, 0
	s_add_u32 s14, s88, 0xeaf0700
	s_addc_u32 s15, s89, 0
	s_add_u32 s16, s88, 0xeaf0800
	s_addc_u32 s17, s89, 0
	s_add_u32 s20, s88, 0xeaf0900
	s_addc_u32 s21, s89, 0
	s_add_u32 s22, s88, 0xeaf0a00
	s_addc_u32 s23, s89, 0
	s_add_u32 s24, s88, 0xeaf0b00
	s_addc_u32 s25, s89, 0
	s_add_u32 s26, s88, 0xeaf0c00
	s_addc_u32 s27, s89, 0
	s_add_u32 s28, s88, 0xeaf0d00
	s_addc_u32 s29, s89, 0
	s_add_u32 s30, s88, 0xeaf0e00
	s_addc_u32 s31, s89, 0
	s_add_u32 s34, s88, 0xeaf0f00
	s_addc_u32 s35, s89, 0
	s_add_u32 s36, s88, 0xeaf1000
	s_addc_u32 s37, s89, 0
	s_add_u32 s38, s88, 0xeaf1100
	s_addc_u32 s39, s89, 0
	s_add_u32 s40, s88, 0xeaf1200
	s_addc_u32 s41, s89, 0
	s_mul_i32 s2, s93, s95
	s_add_u32 s42, s88, 0xeaf1300
	s_mul_i32 s2, s2, s92
	s_addc_u32 s43, s89, 0
	s_mov_b32 s33, 1
	v_mov_b32_e32 v16, 0
	s_branch .LBB0_464

.LBB0_808:
	s_cmp_gt_i32 s91, 4
	s_cselect_b64 s[0:1], -1, 0
	s_and_b64 s[4:5], s[42:43], s[0:1]
	s_andn2_b64 vcc, exec, s[4:5]
	s_cbranch_vccnz .LBB0_862
	s_waitcnt vmcnt(0)
	s_barrier
	s_and_saveexec_b64 s[4:5], s[18:19]
	s_cbranch_execz .LBB0_861
	s_add_i32 s2, 0, 0x113f0
	s_waitcnt vmcnt(7)
	v_mov_b32_e32 v0, s2
	buffer_inv sc1
	s_waitcnt vmcnt(0) expcnt(0) lgkmcnt(0)
	ds_read_b32 v2, v0
	s_add_i32 s2, 0, 0x113f4
	v_mov_b32_e32 v0, s2
	ds_read_b32 v0, v0
	s_waitcnt lgkmcnt(1)
	v_cmp_ne_u32_e32 vcc, 0, v2
	s_cbranch_vccnz .LBB0_825
	s_add_u32 s6, s88, 0xeaf0200
	s_addc_u32 s7, s89, 0
	s_add_u32 s8, s88, 0xeaf0400
	s_addc_u32 s9, s89, 0
	s_add_u32 s10, s88, 0xeaf0500
	s_addc_u32 s11, s89, 0
	s_add_u32 s12, s88, 0xeaf0600
	s_addc_u32 s13, s89, 0
	s_add_u32 s14, s88, 0xeaf0700
	s_addc_u32 s15, s89, 0
	s_add_u32 s16, s88, 0xeaf0800
	s_addc_u32 s17, s89, 0
	s_add_u32 s20, s88, 0xeaf0900
	s_addc_u32 s21, s89, 0
	s_add_u32 s22, s88, 0xeaf0a00
	s_addc_u32 s23, s89, 0
	s_add_u32 s24, s88, 0xeaf0b00
	s_addc_u32 s25, s89, 0
	s_add_u32 s26, s88, 0xeaf0c00
	s_addc_u32 s27, s89, 0
	s_add_u32 s28, s88, 0xeaf0d00
	s_addc_u32 s29, s89, 0
	s_add_u32 s30, s88, 0xeaf0e00
	s_addc_u32 s31, s89, 0
	s_add_u32 s34, s88, 0xeaf0f00
	s_addc_u32 s35, s89, 0
	s_add_u32 s36, s88, 0xeaf1000
	s_addc_u32 s37, s89, 0
	s_add_u32 s38, s88, 0xeaf1100
	s_addc_u32 s39, s89, 0
	s_add_u32 s40, s88, 0xeaf1200
	s_addc_u32 s41, s89, 0
	s_mul_i32 s2, s93, s95
	s_add_u32 s42, s88, 0xeaf1300
	s_mul_i32 s2, s2, s92
	s_addc_u32 s43, s89, 0
	s_mov_b32 s33, 1
	v_mov_b32_e32 v16, 0
	s_branch .LBB0_813

.LBB0_865:
	s_cmp_gt_i32 s91, 5
	s_cselect_b64 s[0:1], -1, 0
	s_and_b64 s[4:5], s[38:39], s[0:1]
	s_andn2_b64 vcc, exec, s[4:5]
	s_cbranch_vccnz .LBB0_919
	s_waitcnt vmcnt(0)
	s_barrier
	s_and_saveexec_b64 s[4:5], s[18:19]
	s_cbranch_execz .LBB0_918
	s_add_i32 s2, 0, 0x113f0
	s_waitcnt vmcnt(7)
	v_mov_b32_e32 v0, s2
	buffer_inv sc1
	s_waitcnt vmcnt(0) expcnt(0) lgkmcnt(0)
	ds_read_b32 v2, v0
	s_add_i32 s2, 0, 0x113f4
	v_mov_b32_e32 v0, s2
	ds_read_b32 v0, v0
	s_waitcnt lgkmcnt(1)
	v_cmp_ne_u32_e32 vcc, 0, v2
	s_cbranch_vccnz .LBB0_882
	s_add_u32 s6, s88, 0xeaf0200
	s_addc_u32 s7, s89, 0
	s_add_u32 s8, s88, 0xeaf0400
	s_addc_u32 s9, s89, 0
	s_add_u32 s10, s88, 0xeaf0500
	s_addc_u32 s11, s89, 0
	s_add_u32 s12, s88, 0xeaf0600
	s_addc_u32 s13, s89, 0
	s_add_u32 s14, s88, 0xeaf0700
	s_addc_u32 s15, s89, 0
	s_add_u32 s16, s88, 0xeaf0800
	s_addc_u32 s17, s89, 0
	s_add_u32 s20, s88, 0xeaf0900
	s_addc_u32 s21, s89, 0
	s_add_u32 s22, s88, 0xeaf0a00
	s_addc_u32 s23, s89, 0
	s_add_u32 s24, s88, 0xeaf0b00
	s_addc_u32 s25, s89, 0
	s_add_u32 s26, s88, 0xeaf0c00
	s_addc_u32 s27, s89, 0
	s_add_u32 s28, s88, 0xeaf0d00
	s_addc_u32 s29, s89, 0
	s_add_u32 s30, s88, 0xeaf0e00
	s_addc_u32 s31, s89, 0
	s_add_u32 s34, s88, 0xeaf0f00
	s_addc_u32 s35, s89, 0
	s_add_u32 s38, s88, 0xeaf1000
	s_addc_u32 s39, s89, 0
	s_add_u32 s40, s88, 0xeaf1100
	s_addc_u32 s41, s89, 0
	s_add_u32 s42, s88, 0xeaf1200
	s_addc_u32 s43, s89, 0
	s_mul_i32 s2, s93, s95
	s_add_u32 s44, s88, 0xeaf1300
	s_mul_i32 s2, s2, s92
	s_addc_u32 s45, s89, 0
	s_mov_b32 s33, 1
	v_mov_b32_e32 v16, 0
	s_branch .LBB0_870

.LBB0_955:
	s_cmp_gt_i32 s91, 6
	s_cselect_b64 s[0:1], -1, 0
	s_and_b64 s[4:5], s[4:5], s[0:1]
	s_andn2_b64 vcc, exec, s[4:5]
	s_cbranch_vccnz .LBB0_1009
	s_waitcnt vmcnt(0)
	s_barrier
	s_and_saveexec_b64 s[4:5], s[18:19]
	s_cbranch_execz .LBB0_1008
	s_add_i32 s2, 0, 0x113f0
	s_waitcnt vmcnt(7)
	v_mov_b32_e32 v0, s2
	buffer_inv sc1
	s_waitcnt vmcnt(0) expcnt(0) lgkmcnt(0)
	ds_read_b32 v2, v0
	s_add_i32 s2, 0, 0x113f4
	v_mov_b32_e32 v0, s2
	ds_read_b32 v0, v0
	s_waitcnt lgkmcnt(1)
	v_cmp_ne_u32_e32 vcc, 0, v2
	s_cbranch_vccnz .LBB0_972
	s_add_u32 s6, s88, 0xeaf0200
	s_addc_u32 s7, s89, 0
	s_add_u32 s8, s88, 0xeaf0400
	s_addc_u32 s9, s89, 0
	s_add_u32 s10, s88, 0xeaf0500
	s_addc_u32 s11, s89, 0
	s_add_u32 s12, s88, 0xeaf0600
	s_addc_u32 s13, s89, 0
	s_add_u32 s14, s88, 0xeaf0700
	s_addc_u32 s15, s89, 0
	s_add_u32 s16, s88, 0xeaf0800
	s_addc_u32 s17, s89, 0
	s_add_u32 s20, s88, 0xeaf0900
	s_addc_u32 s21, s89, 0
	s_add_u32 s22, s88, 0xeaf0a00
	s_addc_u32 s23, s89, 0
	s_add_u32 s24, s88, 0xeaf0b00
	s_addc_u32 s25, s89, 0
	s_add_u32 s26, s88, 0xeaf0c00
	s_addc_u32 s27, s89, 0
	s_add_u32 s28, s88, 0xeaf0d00
	s_addc_u32 s29, s89, 0
	s_add_u32 s30, s88, 0xeaf0e00
	s_addc_u32 s31, s89, 0
	s_add_u32 s34, s88, 0xeaf0f00
	s_addc_u32 s35, s89, 0
	s_add_u32 s38, s88, 0xeaf1000
	s_addc_u32 s39, s89, 0
	s_add_u32 s40, s88, 0xeaf1100
	s_addc_u32 s41, s89, 0
	s_add_u32 s42, s88, 0xeaf1200
	s_addc_u32 s43, s89, 0
	s_mul_i32 s2, s93, s95
	s_add_u32 s44, s88, 0xeaf1300
	s_mul_i32 s2, s2, s92
	s_addc_u32 s45, s89, 0
	s_mov_b32 s33, 1
	v_mov_b32_e32 v16, 0
	s_branch .LBB0_960

.LBB0_1030:
	s_cmp_gt_i32 s91, 7
	s_cselect_b64 s[0:1], -1, 0
	s_and_b64 s[4:5], s[4:5], s[0:1]
	s_andn2_b64 vcc, exec, s[4:5]
	s_cbranch_vccnz .LBB0_1084
	s_waitcnt vmcnt(0)
	s_barrier
	s_and_saveexec_b64 s[4:5], s[18:19]
	s_cbranch_execz .LBB0_1083
	s_add_i32 s2, 0, 0x113f0
	s_waitcnt vmcnt(7)
	v_mov_b32_e32 v0, s2
	buffer_inv sc1
	s_waitcnt vmcnt(0) expcnt(0) lgkmcnt(0)
	ds_read_b32 v2, v0
	s_add_i32 s2, 0, 0x113f4
	v_mov_b32_e32 v0, s2
	ds_read_b32 v0, v0
	s_waitcnt lgkmcnt(1)
	v_cmp_ne_u32_e32 vcc, 0, v2
	s_cbranch_vccnz .LBB0_1047
	s_add_u32 s6, s88, 0xeaf0200
	s_addc_u32 s7, s89, 0
	s_add_u32 s8, s88, 0xeaf0400
	s_addc_u32 s9, s89, 0
	s_add_u32 s10, s88, 0xeaf0500
	s_addc_u32 s11, s89, 0
	s_add_u32 s12, s88, 0xeaf0600
	s_addc_u32 s13, s89, 0
	s_add_u32 s14, s88, 0xeaf0700
	s_addc_u32 s15, s89, 0
	s_add_u32 s16, s88, 0xeaf0800
	s_addc_u32 s17, s89, 0
	s_add_u32 s20, s88, 0xeaf0900
	s_addc_u32 s21, s89, 0
	s_add_u32 s22, s88, 0xeaf0a00
	s_addc_u32 s23, s89, 0
	s_add_u32 s24, s88, 0xeaf0b00
	s_addc_u32 s25, s89, 0
	s_add_u32 s26, s88, 0xeaf0c00
	s_addc_u32 s27, s89, 0
	s_add_u32 s28, s88, 0xeaf0d00
	s_addc_u32 s29, s89, 0
	s_add_u32 s30, s88, 0xeaf0e00
	s_addc_u32 s31, s89, 0
	s_add_u32 s34, s88, 0xeaf0f00
	s_addc_u32 s35, s89, 0
	s_add_u32 s36, s88, 0xeaf1000
	s_addc_u32 s37, s89, 0
	s_add_u32 s38, s88, 0xeaf1100
	s_addc_u32 s39, s89, 0
	s_add_u32 s40, s88, 0xeaf1200
	s_addc_u32 s41, s89, 0
	s_mul_i32 s2, s93, s95
	s_add_u32 s42, s88, 0xeaf1300
	s_mul_i32 s2, s2, s92
	s_addc_u32 s43, s89, 0
	s_mov_b32 s33, 1
	v_mov_b32_e32 v16, 0
	s_branch .LBB0_1035

.LBB0_1112:
	s_cmp_gt_i32 s91, 8
	s_cselect_b64 s[0:1], -1, 0
	s_and_b64 s[4:5], s[10:11], s[0:1]
	s_andn2_b64 vcc, exec, s[4:5]
	s_cbranch_vccnz .LBB0_1166
	s_waitcnt vmcnt(0)
	s_barrier
	s_and_saveexec_b64 s[4:5], s[18:19]
	s_cbranch_execz .LBB0_1165
	s_add_i32 s2, 0, 0x113f0
	s_waitcnt vmcnt(7)
	v_mov_b32_e32 v0, s2
	buffer_inv sc1
	s_waitcnt vmcnt(0) expcnt(0) lgkmcnt(0)
	ds_read_b32 v2, v0
	s_add_i32 s2, 0, 0x113f4
	v_mov_b32_e32 v0, s2
	ds_read_b32 v0, v0
	s_waitcnt lgkmcnt(1)
	v_cmp_ne_u32_e32 vcc, 0, v2
	s_cbranch_vccnz .LBB0_1129
	s_add_u32 s6, s88, 0xeaf0200
	s_addc_u32 s7, s89, 0
	s_add_u32 s10, s88, 0xeaf0400
	s_addc_u32 s11, s89, 0
	s_add_u32 s12, s88, 0xeaf0500
	s_addc_u32 s13, s89, 0
	s_add_u32 s14, s88, 0xeaf0600
	s_addc_u32 s15, s89, 0
	s_add_u32 s16, s88, 0xeaf0700
	s_addc_u32 s17, s89, 0
	s_add_u32 s18, s88, 0xeaf0800
	s_addc_u32 s19, s89, 0
	s_add_u32 s20, s88, 0xeaf0900
	s_addc_u32 s21, s89, 0
	s_add_u32 s22, s88, 0xeaf0a00
	s_addc_u32 s23, s89, 0
	s_add_u32 s24, s88, 0xeaf0b00
	s_addc_u32 s25, s89, 0
	s_add_u32 s26, s88, 0xeaf0c00
	s_addc_u32 s27, s89, 0
	s_add_u32 s28, s88, 0xeaf0d00
	s_addc_u32 s29, s89, 0
	s_add_u32 s30, s88, 0xeaf0e00
	s_addc_u32 s31, s89, 0
	s_add_u32 s34, s88, 0xeaf0f00
	s_addc_u32 s35, s89, 0
	s_add_u32 s36, s88, 0xeaf1000
	s_addc_u32 s37, s89, 0
	s_add_u32 s38, s88, 0xeaf1100
	s_addc_u32 s39, s89, 0
	s_add_u32 s40, s88, 0xeaf1200
	s_addc_u32 s41, s89, 0
	s_mul_i32 s2, s93, s95
	s_add_u32 s42, s88, 0xeaf1300
	s_mul_i32 s2, s2, s92
	s_addc_u32 s43, s89, 0
	s_mov_b32 s33, 1
	v_mov_b32_e32 v16, 0
	s_branch .LBB0_1117

.LBB0_1131:
	s_or_b64 exec, exec, s[12:13]
	v_cvt_f32_u32_e32 v4, v2
	s_waitcnt vmcnt(0)
	v_readfirstlane_b32 s2, v3
	v_sub_u32_e32 v3, 0, v2
	v_rcp_iflag_f32_e32 v4, v4
	v_add_u32_e32 v5, s2, v1
	v_mul_f32_e32 v4, 0x4f7ffffe, v4
	v_cvt_u32_f32_e32 v4, v4
	v_mul_lo_u32 v1, v3, v4
	v_mul_hi_u32 v1, v4, v1
	v_add_u32_e32 v1, v4, v1
	v_mul_hi_u32 v1, v5, v1
	v_mul_lo_u32 v3, v1, v2
	v_sub_u32_e32 v3, v5, v3
	v_add_u32_e32 v4, 1, v1
	v_cmp_ge_u32_e32 vcc, v3, v2
	s_nop 1
	v_cndmask_b32_e32 v1, v1, v4, vcc
	v_sub_u32_e32 v4, v3, v2
	v_cndmask_b32_e32 v3, v3, v4, vcc
	v_add_u32_e32 v4, 1, v1
	v_cmp_ge_u32_e32 vcc, v3, v2
	v_add_u32_e32 v3, 1, v5
	s_nop 0
	v_cndmask_b32_e32 v1, v1, v4, vcc
	v_mul_lo_u32 v4, v2, v1
	v_add_u32_e32 v2, v4, v2
	v_cmp_ne_u32_e32 vcc, v3, v2
	s_and_saveexec_b64 s[2:3], vcc
	s_xor_b64 s[10:11], exec, s[2:3]
	s_cbranch_execz .LBB0_1145
	s_waitcnt lgkmcnt(0)
	v_add_u32_e32 v1, 1, v1
	v_mul_lo_u32 v1, v1, v0
	v_mov_b32_e32 v0, 0
	s_add_u32 s16, s88, 0xeaf3400
	s_addc_u32 s17, s89, 0
	global_load_dword v0, v0, s[16:17] sc1
	s_waitcnt vmcnt(0)
	v_cmp_lt_u32_e32 vcc, v0, v1
	s_and_saveexec_b64 s[12:13], vcc
	s_cbranch_execz .LBB0_1144
	s_add_u32 s14, s88, 0xeaf0200
	s_addc_u32 s15, s89, 0
	s_mov_b32 s2, 1
	s_mov_b64 s[18:19], 0
	v_mov_b32_e32 v0, 0
	s_branch .LBB0_1135

.LBB0_1137:
	global_load_dword v2, v0, s[16:17] sc1
	s_add_i32 s2, s2, 1
	s_mov_b64 s[24:25], -1
	s_waitcnt vmcnt(0)
	v_cmp_ge_u32_e32 vcc, v2, v1
	s_orn2_b64 s[22:23], vcc, exec
	s_branch .LBB0_1134

.LBB0_1148:
	s_or_b64 exec, exec, s[12:13]
	v_cvt_f32_u32_e32 v3, v0
	s_waitcnt vmcnt(0)
	v_readfirstlane_b32 s2, v2
	s_add_u32 s12, s88, 0xeaf3500
	s_addc_u32 s13, s89, 0
	v_rcp_iflag_f32_e32 v3, v3
	v_add_u32_e32 v1, s2, v1
	v_add_u32_e32 v4, 1, v1
	s_mov_b64 s[14:15], -1
	v_mul_f32_e32 v2, 0x4f7ffffe, v3
	v_cvt_u32_f32_e32 v2, v2
	v_sub_u32_e32 v3, 0, v0
	v_mul_lo_u32 v3, v3, v2
	v_mul_hi_u32 v3, v2, v3
	v_add_u32_e32 v2, v2, v3
	v_mul_hi_u32 v2, v1, v2
	v_mul_lo_u32 v3, v2, v0
	v_sub_u32_e32 v1, v1, v3
	v_add_u32_e32 v5, 1, v2
	v_cmp_ge_u32_e32 vcc, v1, v0
	v_sub_u32_e32 v3, v1, v0
	s_nop 0
	v_cndmask_b32_e32 v2, v2, v5, vcc
	v_cndmask_b32_e32 v1, v1, v3, vcc
	v_add_u32_e32 v3, 1, v2
	v_cmp_ge_u32_e32 vcc, v1, v0
	s_nop 1
	v_cndmask_b32_e32 v2, v2, v3, vcc
	v_mul_lo_u32 v1, v0, v2
	v_add_u32_e32 v0, v1, v0
	v_cmp_ne_u32_e32 vcc, v4, v0
	v_mov_b32_e32 v3, v0
	s_add_u32 s98, s88, 0xeaf3400
	s_addc_u32 s99, s89, 0
	v_mov_b64_e32 v[0:1], s[12:13]
	s_and_saveexec_b64 s[10:11], vcc
	s_cbranch_execz .LBB0_1160
	v_mov_b32_e32 v0, 0
	global_load_dword v1, v0, s[98:99] sc1
	s_mov_b64 s[18:19], 0
	s_waitcnt vmcnt(0)
	v_cmp_lt_u32_e32 vcc, v1, v3
	s_and_saveexec_b64 s[16:17], vcc
	s_cbranch_execz .LBB0_1159
	s_add_u32 s14, s88, 0xeaf0200
	s_addc_u32 s15, s89, 0
	s_mov_b32 s2, 1
	s_branch .LBB0_1152

.LBB0_1162:
	s_or_b64 exec, exec, s[10:11]
	s_mov_b64 s[10:11], exec
	v_mbcnt_lo_u32_b32 v0, s10, 0
	v_mbcnt_hi_u32_b32 v0, s11, v0
	v_cmp_eq_u32_e32 vcc, 0, v0
	s_waitcnt vmcnt(0)
	s_and_saveexec_b64 s[12:13], vcc
	s_cbranch_execz .LBB0_1164
	s_bcnt1_i32_b64 s2, s[10:11]
	v_mov_b32_e32 v0, 0x2000
	v_mov_b32_e32 v1, s2
	global_atomic_add v0, v1, s[6:7] offset:1024

	.amdhsa_kernel _Z4mega6Params
		.amdhsa_group_segment_fixed_size 0
		.amdhsa_private_segment_fixed_size 0
		.amdhsa_kernarg_size 480
		.amdhsa_user_sgpr_count 2
		.amdhsa_user_sgpr_dispatch_ptr 0
		.amdhsa_user_sgpr_queue_ptr 0
		.amdhsa_user_sgpr_kernarg_segment_ptr 1
		.amdhsa_user_sgpr_dispatch_id 0
		.amdhsa_user_sgpr_kernarg_preload_length 0
		.amdhsa_user_sgpr_kernarg_preload_offset 0
		.amdhsa_user_sgpr_private_segment_size 0
		.amdhsa_uses_dynamic_stack 0
		.amdhsa_enable_private_segment 0
		.amdhsa_system_sgpr_workgroup_id_x 1
		.amdhsa_system_sgpr_workgroup_id_y 0
		.amdhsa_system_sgpr_workgroup_id_z 0
		.amdhsa_system_sgpr_workgroup_info 0
		.amdhsa_system_vgpr_workitem_id 2
		.amdhsa_next_free_vgpr 256
		.amdhsa_next_free_sgpr 100
		.amdhsa_accum_offset 256
		.amdhsa_reserve_vcc 1
		.amdhsa_float_round_mode_32 0
		.amdhsa_float_round_mode_16_64 0
		.amdhsa_float_denorm_mode_32 3
		.amdhsa_float_denorm_mode_16_64 3
		.amdhsa_dx10_clamp 1
		.amdhsa_ieee_mode 1
		.amdhsa_fp16_overflow 0
		.amdhsa_tg_split 0
		.amdhsa_exception_fp_ieee_invalid_op 0
		.amdhsa_exception_fp_denorm_src 0
		.amdhsa_exception_fp_ieee_div_zero 0
		.amdhsa_exception_fp_ieee_overflow 0
		.amdhsa_exception_fp_ieee_underflow 0
		.amdhsa_exception_fp_ieee_inexact 0
		.amdhsa_exception_int_div_zero 0
	.end_amdhsa_kernel

amdhsa.kernels:
  - .agpr_count:     0
    .args:
      - .offset:         0
        .size:           224
        .value_kind:     by_value
      - .offset:         224
        .size:           4
        .value_kind:     hidden_block_count_x
      - .offset:         228
        .size:           4
        .value_kind:     hidden_block_count_y
      - .offset:         232
        .size:           4
        .value_kind:     hidden_block_count_z
      - .offset:         236
        .size:           2
        .value_kind:     hidden_group_size_x
      - .offset:         238
        .size:           2
        .value_kind:     hidden_group_size_y
      - .offset:         240
        .size:           2
        .value_kind:     hidden_group_size_z
      - .offset:         242
        .size:           2
        .value_kind:     hidden_remainder_x
      - .offset:         244
        .size:           2
        .value_kind:     hidden_remainder_y
      - .offset:         246
        .size:           2
        .value_kind:     hidden_remainder_z
      - .offset:         264
        .size:           8
        .value_kind:     hidden_global_offset_x
      - .offset:         272
        .size:           8
        .value_kind:     hidden_global_offset_y
      - .offset:         280
        .size:           8
        .value_kind:     hidden_global_offset_z
      - .offset:         288
        .size:           2
        .value_kind:     hidden_grid_dims
      - .offset:         312
        .size:           8
        .value_kind:     hidden_multigrid_sync_arg
      - .offset:         344
        .size:           4
        .value_kind:     hidden_dynamic_lds_size
    .group_segment_fixed_size: 0
    .kernarg_segment_align: 8
    .kernarg_segment_size: 480
    .language:       OpenCL C
    .language_version:
      - 2
      - 0
    .max_flat_workgroup_size: 256
    .name:           _Z4mega6Params
    .private_segment_fixed_size: 0
    .sgpr_count:     106
    .sgpr_spill_count: 2
    .symbol:         _Z4mega6Params.kd
    .uniform_work_group_size: 1
    .uses_dynamic_stack: false
    .vgpr_count:     256
    .vgpr_spill_count: 0
    .wavefront_size: 64
